# steady attention step issue-slot trimming: drop no-op phase-A waits, merge hoisted PV waits, SGPR running-base tile DMAs (no VALU64, no s_nop), s3 rescale flag, fillers instead of s_nop before permlan
# speedup vs baseline: 1.0133x; 1.0079x over previous
.LBB0_971:
	s_and_b32 s16, s41, 0x3fffffc0
	s_cmp_lg_u32 0, -1
	v_lshlrev_b32_e32 v3, 1, v52
	s_cselect_b32 s3, 0, 0
	v_lshlrev_b32_e32 v4, 4, v52
	v_and_b32_e32 v3, 32, v3
	s_add_i32 s17, s3, 0x6000
	v_and_b32_e32 v4, 0xc0, v4
	v_add_u32_e32 v54, s17, v3
	v_lshl_or_b32 v55, v221, 8, v4
	v_add_u32_e32 v3, 0, v3
	v_add3_u32 v242, v3, v53, v55
	v_add3_u32 v238, v54, v53, v55
	v_max3_f32 v53, v34, v35, v18
	v_max3_f32 v54, v36, v37, v19
	s_lshl_b32 s16, s16, 2
	v_max3_f32 v53, v53, v20, v21
	v_max3_f32 v54, v54, v40, v41
	s_add_i32 s94, s16, 0
	v_max3_f32 v53, v53, v38, v39
	v_max3_f32 v54, v54, v24, v25
	s_add_i32 s17, s43, 0x100
	v_max3_f32 v53, v53, v22, v23
	v_max3_f32 v54, v54, v44, v45
	s_add_i32 s94, s94, 0x12000
	v_max3_f32 v53, v53, v42, v43
	v_max3_f32 v54, v54, v28, v29
	s_mov_b32 s6, 1
	v_max3_f32 v53, v53, v26, v27
	v_max3_f32 v54, v54, v48, v49
	s_mov_b32 s44, 0
	v_max3_f32 v53, v53, v46, v47
	v_max3_f32 v54, v54, v32, v33
	v_mov_b32_e32 v3, v2
	v_max3_f32 v53, v53, v30, v31
	v_mov_b32_e32 v4, v2
	v_max_f32_e32 v53, v53, v54
	v_mov_b32_e32 v5, v2
	v_mov_b32_e32 v54, v53
	s_nop 1
	v_permlane32_swap_b32_e32 v53, v54
	v_max_f32_e32 v53, v53, v54
	v_mov_b32_e32 v6, v2
	v_add_f32_e32 v240, v225, v53
	v_sub_f32_e32 v18, v18, v53
	v_sub_f32_e32 v19, v19, v53
	v_sub_f32_e32 v34, v34, v53
	v_sub_f32_e32 v35, v35, v53
	v_sub_f32_e32 v36, v36, v53
	s_nop 0
	v_xor_b32_e32 v66, 0x80000000, v240
	v_mov_b32_e32 v67, v66
	v_mov_b32_e32 v68, v66
	v_mov_b32_e32 v69, v66
	v_mov_b32_e32 v70, v66
	v_mov_b32_e32 v71, v66
	v_mov_b32_e32 v72, v66
	v_mov_b32_e32 v73, v66
	v_mov_b32_e32 v74, v66
	v_mov_b32_e32 v75, v66
	v_mov_b32_e32 v76, v66
	v_mov_b32_e32 v77, v66
	v_mov_b32_e32 v78, v66
	v_mov_b32_e32 v79, v66
	v_mov_b32_e32 v80, v66
	v_mov_b32_e32 v81, v66
	s_waitcnt vmcnt(0) lgkmcnt(0)
	s_barrier
	v_exp_f32_e32 v82, v18
	v_exp_f32_e32 v83, v19
	v_lshl_add_u64 v[18:19], v[226:227], 0, s[28:29]
	s_mov_b32 s16, m0
	s_mov_b32 m0, s83
	s_nop 0
	global_load_lds_dwordx4 v[18:19], off
	s_mov_b32 m0, s16
	s_add_i32 s16, s3, s2
	v_lshl_add_u64 v[18:19], v[50:51], 0, s[24:25]
	s_add_i32 s2, s16, 0xa000
	s_mov_b32 s3, m0
	s_mov_b32 m0, s2
	s_nop 0
	global_load_lds_dwordx4 v[18:19], off
	s_mov_b32 m0, s3
	s_mov_b64 s[2:3], 0x10080
	v_lshl_add_u64 v[18:19], v[50:51], 0, s[2:3]
	s_add_i32 s16, s16, 0xc000
	s_mov_b32 s2, m0
	s_mov_b32 m0, s16
	s_nop 0
	global_load_lds_dwordx4 v[18:19], off
	s_mov_b32 m0, s2
	ds_read_b128 v[206:209], v241 offset:8192
	ds_read_b128 v[202:205], v241 offset:8704
	ds_read_b128 v[198:201], v241 offset:10240
	ds_read_b128 v[194:197], v241 offset:10752
	ds_read_b128 v[190:193], v241 offset:12288
	ds_read_b128 v[186:189], v241 offset:12800
	ds_read_b128 v[182:185], v241 offset:14336
	ds_read_b128 v[178:181], v241 offset:14848
	v_sub_f32_e32 v20, v20, v53
	v_sub_f32_e32 v37, v37, v53
	v_sub_f32_e32 v21, v21, v53
	v_sub_f32_e32 v38, v38, v53
	v_sub_f32_e32 v22, v22, v53
	v_sub_f32_e32 v39, v39, v53
	v_sub_f32_e32 v23, v23, v53
	v_sub_f32_e32 v40, v40, v53
	v_sub_f32_e32 v24, v24, v53
	v_sub_f32_e32 v41, v41, v53
	v_sub_f32_e32 v25, v25, v53
	v_sub_f32_e32 v42, v42, v53
	v_sub_f32_e32 v26, v26, v53
	v_sub_f32_e32 v43, v43, v53
	v_sub_f32_e32 v27, v27, v53
	v_sub_f32_e32 v44, v44, v53
	v_sub_f32_e32 v28, v28, v53
	v_sub_f32_e32 v45, v45, v53
	v_sub_f32_e32 v29, v29, v53
	v_sub_f32_e32 v46, v46, v53
	v_sub_f32_e32 v30, v30, v53
	v_sub_f32_e32 v47, v47, v53
	v_sub_f32_e32 v31, v31, v53
	v_sub_f32_e32 v48, v48, v53
	v_sub_f32_e32 v32, v32, v53
	v_sub_f32_e32 v49, v49, v53
	v_sub_f32_e32 v33, v33, v53
	v_exp_f32_e32 v98, v34
	v_exp_f32_e32 v99, v35
	v_exp_f32_e32 v100, v36
	v_exp_f32_e32 v101, v37
	v_exp_f32_e32 v102, v38
	v_exp_f32_e32 v103, v39
	v_exp_f32_e32 v104, v40
	v_exp_f32_e32 v105, v41
	v_exp_f32_e32 v106, v42
	v_exp_f32_e32 v107, v43
	v_exp_f32_e32 v108, v44
	v_exp_f32_e32 v109, v45
	v_exp_f32_e32 v110, v46
	v_exp_f32_e32 v111, v47
	v_exp_f32_e32 v112, v48
	v_exp_f32_e32 v113, v49
	v_exp_f32_e32 v84, v20
	v_exp_f32_e32 v85, v21
	v_exp_f32_e32 v86, v22
	v_exp_f32_e32 v87, v23
	v_exp_f32_e32 v88, v24
	v_exp_f32_e32 v89, v25
	v_exp_f32_e32 v90, v26
	v_exp_f32_e32 v91, v27
	v_exp_f32_e32 v92, v28
	v_exp_f32_e32 v93, v29
	v_exp_f32_e32 v94, v30
	v_exp_f32_e32 v95, v31
	v_exp_f32_e32 v96, v32
	v_exp_f32_e32 v97, v33
	s_waitcnt vmcnt(3) lgkmcnt(0)
	s_barrier
	v_and_b32_e32 v18, 3, v52
	v_mov_b32_e32 v7, v2
	v_mov_b32_e32 v8, v2
	v_mov_b32_e32 v9, v2
	v_mov_b32_e32 v10, v2
	v_mov_b32_e32 v11, v2
	v_mov_b32_e32 v12, v2
	v_mov_b32_e32 v13, v2
	v_mov_b32_e32 v14, v2
	v_mov_b32_e32 v15, v2
	v_mov_b32_e32 v16, v2
	v_mov_b32_e32 v17, v2
	s_lshr_b32 s95, s17, 6
	s_andn2_b64 vcc, exec, s[0:1]
	v_cmp_gt_u32_e64 s[0:1], 32, v223
	v_lshlrev_b32_e32 v243, 4, v221
	v_lshl_add_u32 v237, v234, 2, s94
	v_lshlrev_b32_e32 v224, 4, v18
	s_cbranch_vccnz .LBB0_987
	s_lshl_b32 s2, s41, 8
	s_and_b32 s2, s2, 0xc000
	v_lshl_add_u64 v[18:19], s[4:5], 1, v[224:225]
	v_lshl_or_b32 v20, v220, 10, s2
	v_mov_b32_e32 v21, v225
	v_lshl_add_u64 v[18:19], v[18:19], 0, v[20:21]
	v_lshl_add_u64 v[214:215], s[22:23], 0, v[18:19]
	v_mov_b64_e32 v[64:65], v[16:17]
	v_mov_b64_e32 v[48:49], v[16:17]
	v_mov_b64_e32 v[32:33], v[16:17]
	s_add_i32 s42, s95, -5
	s_movk_i32 s46, 0x2000
	v_add_u32_e32 v228, 0x2000, v238
	s_movk_i32 s44, 0x4000
	s_mov_b32 s2, 0
	v_mov_b32_e32 v244, 0
	s_mov_b64 s[16:17], 0
	v_mov_b64_e32 v[62:63], v[14:15]
	v_mov_b64_e32 v[60:61], v[12:13]
	v_mov_b64_e32 v[58:59], v[10:11]
	v_mov_b64_e32 v[56:57], v[8:9]
	v_mov_b64_e32 v[54:55], v[6:7]
	v_mov_b64_e32 v[52:53], v[4:5]
	v_mov_b64_e32 v[50:51], v[2:3]
	v_mov_b64_e32 v[46:47], v[14:15]
	v_mov_b64_e32 v[44:45], v[12:13]
	v_mov_b64_e32 v[42:43], v[10:11]
	v_mov_b64_e32 v[40:41], v[8:9]
	v_mov_b64_e32 v[38:39], v[6:7]
	v_mov_b64_e32 v[36:37], v[4:5]
	v_mov_b64_e32 v[34:35], v[2:3]
	v_mov_b64_e32 v[30:31], v[14:15]
	v_mov_b64_e32 v[28:29], v[12:13]
	v_mov_b64_e32 v[26:27], v[10:11]
	v_mov_b64_e32 v[24:25], v[8:9]
	v_mov_b64_e32 v[22:23], v[6:7]
	v_mov_b64_e32 v[20:21], v[4:5]
	v_mov_b64_e32 v[18:19], v[2:3]
	v_readfirstlane_b32 s98, v226
	v_readfirstlane_b32 s99, v227
	v_readfirstlane_b32 s100, v214
	v_readfirstlane_b32 s101, v215
	s_mov_b32 s3, 0
	v_subrev_u32_e32 v218, s98, v226
	v_subrev_u32_e32 v219, s100, v214
	s_add_u32 s98, s98, s16
	s_addc_u32 s99, s99, s17
	s_add_u32 s98, s98, s30
	s_addc_u32 s99, s99, s31
	s_add_u32 s100, s100, s16
	s_addc_u32 s101, s101, s17
	s_add_u32 s100, s100, s34
	s_addc_u32 s101, s101, s35
.LBB0_973:
	s_lshl_b32 s40, s2, 1
	v_add_u32_e32 v216, s40, v242
	ds_read_b64_tr_b16 v[210:211], v216 offset:24576
	ds_read_b64_tr_b16 v[212:213], v216 offset:25088
	v_mfma_f32_32x32x16_bf16 v[130:145], v[206:209], v[174:177], v[66:81]
	v_add_f32_e32 v114, v98, v99
	v_add_f32_e32 v114, v100, v114
	v_add_f32_e32 v114, v101, v114
	v_add_f32_e32 v114, v102, v114
	v_add_f32_e32 v114, v103, v114
	v_cvt_pk_bf16_f32 v158, v98, v99
	v_cvt_pk_bf16_f32 v159, v100, v101
	ds_read_b64_tr_b16 v[206:207], v216 offset:28672
	ds_read_b64_tr_b16 v[208:209], v216 offset:29184
	v_add_f32_e32 v98, v104, v114
	v_mfma_f32_32x32x16_bf16 v[114:129], v[202:205], v[174:177], v[66:81]
	v_add_f32_e32 v98, v105, v98
	v_add_f32_e32 v98, v106, v98
	v_add_f32_e32 v146, v107, v98
	v_cvt_pk_bf16_f32 v160, v102, v103
	v_cvt_pk_bf16_f32 v161, v104, v105
	ds_read_b64_tr_b16 v[98:99], v216 offset:25600
	ds_read_b64_tr_b16 v[100:101], v216 offset:26112
	v_mfma_f32_32x32x16_bf16 v[130:145], v[198:201], v[170:173], v[130:145]
	v_add_f32_e32 v102, v108, v146
	v_add_f32_e32 v102, v109, v102
	v_add_f32_e32 v102, v110, v102
	v_add_f32_e32 v146, v111, v102
	v_cvt_pk_bf16_f32 v154, v106, v107
	v_cvt_pk_bf16_f32 v155, v108, v109
	ds_read_b64_tr_b16 v[102:103], v216 offset:29696
	ds_read_b64_tr_b16 v[104:105], v216 offset:30208
	v_mfma_f32_32x32x16_bf16 v[114:129], v[194:197], v[170:173], v[114:129]
	v_add_f32_e32 v106, v112, v146
	v_add_f32_e32 v106, v113, v106
	v_add_f32_e32 v106, v82, v106
	v_add_f32_e32 v146, v83, v106
	v_cvt_pk_bf16_f32 v156, v110, v111
	v_cvt_pk_bf16_f32 v157, v112, v113
	ds_read_b64_tr_b16 v[106:107], v216 offset:26624
	ds_read_b64_tr_b16 v[108:109], v216 offset:27136
	v_mfma_f32_32x32x16_bf16 v[130:145], v[190:193], v[166:169], v[130:145]
	v_add_f32_e32 v110, v84, v146
	v_add_f32_e32 v110, v85, v110
	v_add_f32_e32 v110, v86, v110
	v_add_f32_e32 v146, v87, v110
	v_cvt_pk_bf16_f32 v150, v82, v83
	v_cvt_pk_bf16_f32 v151, v84, v85
	ds_read_b64_tr_b16 v[110:111], v216 offset:30720
	ds_read_b64_tr_b16 v[112:113], v216 offset:31232
	v_mfma_f32_32x32x16_bf16 v[114:129], v[186:189], v[166:169], v[114:129]
	v_add_f32_e32 v82, v88, v146
	v_add_f32_e32 v82, v89, v82
	v_add_f32_e32 v82, v90, v82
	v_add_f32_e32 v82, v91, v82
	v_cvt_pk_bf16_f32 v152, v86, v87
	v_cvt_pk_bf16_f32 v153, v88, v89
	ds_read_b64_tr_b16 v[86:87], v216 offset:27648
	ds_read_b64_tr_b16 v[88:89], v216 offset:28160
	v_mfma_f32_32x32x16_bf16 v[130:145], v[182:185], v[162:165], v[130:145]
	v_add_f32_e32 v82, v92, v82
	v_add_f32_e32 v82, v93, v82
	v_add_f32_e32 v82, v94, v82
	v_add_f32_e32 v82, v95, v82
	v_cvt_pk_bf16_f32 v146, v90, v91
	v_cvt_pk_bf16_f32 v147, v92, v93
	ds_read_b64_tr_b16 v[90:91], v216 offset:31744
	ds_read_b64_tr_b16 v[92:93], v216 offset:32256
	v_mfma_f32_32x32x16_bf16 v[114:129], v[178:181], v[162:165], v[114:129]
	v_add_f32_e32 v82, v96, v82
	v_add_f32_e32 v82, v97, v82
	v_add_f32_e32 v230, v244, v82
	v_cvt_pk_bf16_f32 v148, v94, v95
	v_cvt_pk_bf16_f32 v149, v96, v97
	s_waitcnt lgkmcnt(8)
	v_mfma_f32_32x32x16_bf16 v[50:65], v[158:161], v[210:213], v[50:65]
	s_add_i32 m0, s46, s83
	s_lshl_b32 s2, s44, 1
	global_load_lds_dwordx4 v218, s[98:99]
	s_add_i32 m0, s2, s84
	s_add_u32 s98, s98, 0x10000
	s_addc_u32 s99, s99, 0
	global_load_lds_dwordx4 v219, s[100:101]
	s_addk_i32 m0, 0x1f80
	v_mfma_f32_32x32x16_bf16 v[34:49], v[158:161], v[206:209], v[34:49]
	global_load_lds_dwordx4 v219, s[100:101] offset:128
	s_add_u32 s100, s100, 0x10000
	s_addc_u32 s101, s101, 0
	v_mfma_f32_32x32x16_bf16 v[50:65], v[154:157], v[98:101], v[50:65]
	v_max_f32_e32 v82, v130, v131
	v_max3_f32 v83, v132, v133, v115
	v_max3_f32 v82, v82, v114, v116
	v_max3_f32 v82, v82, v117, v134
	v_max3_f32 v83, v83, v136, v137
	v_max3_f32 v82, v82, v135, v118
	v_max3_f32 v83, v83, v120, v121
	v_max3_f32 v82, v82, v119, v138
	v_mfma_f32_32x32x16_bf16 v[34:49], v[154:157], v[102:105], v[34:49]
	v_max3_f32 v83, v83, v140, v141
	v_max3_f32 v82, v82, v139, v122
	v_max3_f32 v83, v83, v124, v125
	v_max3_f32 v82, v82, v123, v142
	v_max3_f32 v83, v83, v144, v145
	v_max3_f32 v82, v82, v143, v126
	v_max3_f32 v83, v83, v128, v129
	v_max3_f32 v82, v82, v127, v83
	v_mov_b32_e32 v83, v82
	v_add_u32_e32 v94, s44, v241
	v_add_u32_e32 v102, s40, v228
	v_permlane32_swap_b32_e32 v82, v83
	v_max_f32_e32 v82, v82, v83
	v_cmp_lt_f32_e32 vcc, s87, v82
	s_cbranch_vccnz .LBB0_981
.LBB0_974:
	ds_read_b128 v[82:85], v94
	ds_read_b128 v[198:201], v94 offset:512
	ds_read_b128 v[202:205], v94 offset:2048
	ds_read_b128 v[194:197], v94 offset:2560
	s_waitcnt lgkmcnt(4)
	v_mfma_f32_32x32x16_bf16 v[50:65], v[150:153], v[106:109], v[50:65]
	v_exp_f32_e32 v130, v130
	v_exp_f32_e32 v131, v131
	v_exp_f32_e32 v132, v132
	ds_read_b128 v[190:193], v94 offset:4096
	ds_read_b128 v[186:189], v94 offset:4608
	ds_read_b128 v[182:185], v94 offset:6144
	ds_read_b128 v[178:181], v94 offset:6656
	ds_read_b64_tr_b16 v[98:99],v102 offset:3072
	ds_read_b64_tr_b16 v[100:101],v102 offset:3584
	ds_read_b64_tr_b16 v[94:95],v102 offset:2048
	ds_read_b64_tr_b16 v[96:97],v102 offset:2560
	v_mfma_f32_32x32x16_bf16 v[34:49], v[150:153], v[110:113], v[34:49]
	v_exp_f32_e32 v133, v133
	v_exp_f32_e32 v134, v134
	v_exp_f32_e32 v135, v135
	v_mfma_f32_32x32x16_bf16 v[50:65], v[146:149], v[86:89], v[50:65]
	v_exp_f32_e32 v136, v136
	v_exp_f32_e32 v137, v137
	v_exp_f32_e32 v138, v138
	ds_read_b64_tr_b16 v[86:87],v102 offset:0
	ds_read_b64_tr_b16 v[88:89],v102 offset:512
	v_mfma_f32_32x32x16_bf16 v[34:49], v[146:149], v[90:93], v[34:49]
	v_exp_f32_e32 v139, v139
	v_exp_f32_e32 v140, v140
	v_exp_f32_e32 v141, v141
	ds_read_b64_tr_b16 v[90:91],v102 offset:1024
	ds_read_b64_tr_b16 v[92:93],v102 offset:1536
	s_waitcnt lgkmcnt(6)
	v_mfma_f32_32x32x16_bf16 v[18:33], v[146:149], v[98:101], v[18:33]
	v_exp_f32_e32 v142, v142
	v_exp_f32_e32 v143, v143
	v_exp_f32_e32 v144, v144
	ds_read_b64_tr_b16 v[98:99],v102 offset:7168
	ds_read_b64_tr_b16 v[100:101],v102 offset:7680
	s_waitcnt lgkmcnt(6)
	v_mfma_f32_32x32x16_bf16 v[18:33], v[150:153], v[94:97], v[18:33]
	v_exp_f32_e32 v145, v145
	v_exp_f32_e32 v114, v114
	v_exp_f32_e32 v115, v115
	ds_read_b64_tr_b16 v[94:95],v102 offset:6144
	ds_read_b64_tr_b16 v[96:97],v102 offset:6656
	s_waitcnt lgkmcnt(6)
	v_mfma_f32_32x32x16_bf16 v[18:33], v[158:161], v[86:89], v[18:33]
	v_exp_f32_e32 v116, v116
	v_exp_f32_e32 v117, v117
	v_exp_f32_e32 v118, v118
	ds_read_b64_tr_b16 v[86:87],v102 offset:4096
	ds_read_b64_tr_b16 v[88:89],v102 offset:4608
	s_waitcnt lgkmcnt(6)
	v_mfma_f32_32x32x16_bf16 v[18:33], v[154:157], v[90:93], v[18:33]
	v_exp_f32_e32 v119, v119
	v_exp_f32_e32 v120, v120
	v_exp_f32_e32 v121, v121
	ds_read_b64_tr_b16 v[90:91],v102 offset:5120
	ds_read_b64_tr_b16 v[92:93],v102 offset:5632
	s_waitcnt lgkmcnt(6)
	v_mfma_f32_32x32x16_bf16 v[2:17], v[146:149], v[98:101], v[2:17]
	v_exp_f32_e32 v122, v122
	v_exp_f32_e32 v123, v123
	s_waitcnt vmcnt(3) lgkmcnt(0)
	s_barrier
	v_mfma_f32_32x32x16_bf16 v[2:17], v[150:153], v[94:97], v[2:17]
	v_exp_f32_e32 v124, v124
	v_exp_f32_e32 v125, v125
	v_mfma_f32_32x32x16_bf16 v[2:17], v[158:161], v[86:89], v[2:17]
	v_exp_f32_e32 v126, v126
	v_exp_f32_e32 v127, v127
	v_mfma_f32_32x32x16_bf16 v[2:17], v[154:157], v[90:93], v[2:17]
	v_exp_f32_e32 v128, v128
	v_exp_f32_e32 v129, v129
	s_cmp_eq_u32 s3, 0
	s_cbranch_scc1 .LBB0_976
	s_waitcnt lgkmcnt(0)
	s_mov_b32 s3, 0
	v_add_u32_e32 v229, s94, v243
	ds_read_b128 v[86:89], v229 offset:96
	ds_read_b128 v[90:93], v229 offset:64
	ds_read_b128 v[94:97], v229 offset:32
	ds_read_b128 v[98:101], v229
	s_waitcnt lgkmcnt(3)
	v_pk_mul_f32 v[62:63], v[62:63], v[86:87]
	s_waitcnt lgkmcnt(2)
	v_pk_mul_f32 v[58:59], v[58:59], v[90:91]
	s_waitcnt lgkmcnt(1)
	v_pk_mul_f32 v[54:55], v[54:55], v[94:95]
	v_pk_mul_f32 v[64:65], v[64:65], v[88:89]
	v_pk_mul_f32 v[60:61], v[60:61], v[92:93]
	v_pk_mul_f32 v[56:57], v[56:57], v[96:97]
	s_waitcnt lgkmcnt(0)
	v_pk_mul_f32 v[52:53], v[52:53], v[100:101]
	v_pk_mul_f32 v[50:51], v[50:51], v[98:99]
	v_pk_mul_f32 v[46:47], v[46:47], v[86:87]
	v_pk_mul_f32 v[42:43], v[42:43], v[90:91]
	v_pk_mul_f32 v[38:39], v[38:39], v[94:95]
	v_pk_mul_f32 v[48:49], v[48:49], v[88:89]
	v_pk_mul_f32 v[44:45], v[44:45], v[92:93]
	v_pk_mul_f32 v[40:41], v[40:41], v[96:97]
	v_pk_mul_f32 v[36:37], v[36:37], v[100:101]
	v_pk_mul_f32 v[34:35], v[34:35], v[98:99]
	v_pk_mul_f32 v[30:31], v[30:31], v[86:87]
	v_pk_mul_f32 v[26:27], v[26:27], v[90:91]
	v_pk_mul_f32 v[22:23], v[22:23], v[94:95]
	v_pk_mul_f32 v[32:33], v[32:33], v[88:89]
	v_pk_mul_f32 v[28:29], v[28:29], v[92:93]
	v_pk_mul_f32 v[24:25], v[24:25], v[96:97]
	v_pk_mul_f32 v[20:21], v[20:21], v[100:101]
	v_pk_mul_f32 v[18:19], v[18:19], v[98:99]
	v_pk_mul_f32 v[14:15], v[14:15], v[86:87]
	v_pk_mul_f32 v[10:11], v[10:11], v[90:91]
	v_pk_mul_f32 v[6:7], v[6:7], v[94:95]
	v_pk_mul_f32 v[16:17], v[16:17], v[88:89]
	v_pk_mul_f32 v[12:13], v[12:13], v[92:93]
	v_pk_mul_f32 v[8:9], v[8:9], v[96:97]
	v_pk_mul_f32 v[4:5], v[4:5], v[100:101]
	v_pk_mul_f32 v[2:3], v[2:3], v[98:99]
.LBB0_976:
	s_add_i32 s2, s44, 0x2000
	s_cmpk_lg_i32 s44, 0x4000
	s_cselect_b32 s40, s2, 0
	s_lshl_b32 s45, s46, 1
	v_add_u32_e32 v231, s45, v242
	ds_read_b64_tr_b16 v[210:211], v231 offset:24576
	ds_read_b64_tr_b16 v[212:213], v231 offset:25088
	v_mfma_f32_32x32x16_bf16 v[98:113], v[82:85], v[174:177], v[66:81]
	v_add_f32_e32 v86, v130, v131
	v_add_f32_e32 v86, v132, v86
	v_add_f32_e32 v86, v133, v86
	v_add_f32_e32 v86, v134, v86
	v_add_f32_e32 v86, v135, v86
	v_cvt_pk_bf16_f32 v158, v130, v131
	v_cvt_pk_bf16_f32 v159, v132, v133
	ds_read_b64_tr_b16 v[206:207], v231 offset:28672
	ds_read_b64_tr_b16 v[208:209], v231 offset:29184
	v_add_f32_e32 v82, v136, v86
	v_add_f32_e32 v82, v137, v82
	v_add_f32_e32 v82, v138, v82
	v_add_f32_e32 v146, v139, v82
	v_mfma_f32_32x32x16_bf16 v[82:97], v[198:201], v[174:177], v[66:81]
	v_cvt_pk_bf16_f32 v160, v134, v135
	v_cvt_pk_bf16_f32 v161, v136, v137
	ds_read_b64_tr_b16 v[130:131], v231 offset:25600
	ds_read_b64_tr_b16 v[132:133], v231 offset:26112
	v_mfma_f32_32x32x16_bf16 v[98:113], v[202:205], v[170:173], v[98:113]
	v_add_f32_e32 v134, v140, v146
	v_add_f32_e32 v134, v141, v134
	v_add_f32_e32 v134, v142, v134
	v_add_f32_e32 v146, v143, v134
	v_cvt_pk_bf16_f32 v154, v138, v139
	v_cvt_pk_bf16_f32 v155, v140, v141
	ds_read_b64_tr_b16 v[134:135], v231 offset:29696
	ds_read_b64_tr_b16 v[136:137], v231 offset:30208
	v_mfma_f32_32x32x16_bf16 v[82:97], v[194:197], v[170:173], v[82:97]
	v_add_f32_e32 v138, v144, v146
	v_add_f32_e32 v138, v145, v138
	v_add_f32_e32 v138, v114, v138
	v_add_f32_e32 v146, v115, v138
	v_cvt_pk_bf16_f32 v156, v142, v143
	v_cvt_pk_bf16_f32 v157, v144, v145
	ds_read_b64_tr_b16 v[138:139], v231 offset:26624
	ds_read_b64_tr_b16 v[140:141], v231 offset:27136
	v_mfma_f32_32x32x16_bf16 v[98:113], v[190:193], v[166:169], v[98:113]
	v_add_f32_e32 v142, v116, v146
	v_add_f32_e32 v142, v117, v142
	v_add_f32_e32 v142, v118, v142
	v_add_f32_e32 v142, v119, v142
	v_cvt_pk_bf16_f32 v150, v114, v115
	v_cvt_pk_bf16_f32 v151, v116, v117
	ds_read_b64_tr_b16 v[114:115], v231 offset:30720
	ds_read_b64_tr_b16 v[116:117], v231 offset:31232
	v_mfma_f32_32x32x16_bf16 v[82:97], v[186:189], v[166:169], v[82:97]
	v_add_f32_e32 v142, v120, v142
	v_add_f32_e32 v142, v121, v142
	v_add_f32_e32 v142, v122, v142
	v_add_f32_e32 v142, v123, v142
	v_cvt_pk_bf16_f32 v152, v118, v119
	v_cvt_pk_bf16_f32 v153, v120, v121
	ds_read_b64_tr_b16 v[118:119], v231 offset:27648
	ds_read_b64_tr_b16 v[120:121], v231 offset:28160
	v_mfma_f32_32x32x16_bf16 v[98:113], v[182:185], v[162:165], v[98:113]
	v_add_f32_e32 v142, v124, v142
	v_add_f32_e32 v142, v125, v142
	v_add_f32_e32 v142, v126, v142
	v_add_f32_e32 v142, v127, v142
	v_cvt_pk_bf16_f32 v146, v122, v123
	v_cvt_pk_bf16_f32 v147, v124, v125
	ds_read_b64_tr_b16 v[122:123], v231 offset:31744
	ds_read_b64_tr_b16 v[124:125], v231 offset:32256
	v_mfma_f32_32x32x16_bf16 v[82:97], v[178:181], v[162:165], v[82:97]
	v_add_f32_e32 v142, v128, v142
	v_add_f32_e32 v142, v129, v142
	v_cvt_pk_bf16_f32 v148, v126, v127
	v_cvt_pk_bf16_f32 v149, v128, v129
	s_waitcnt lgkmcnt(8)
	v_mfma_f32_32x32x16_bf16 v[50:65], v[158:161], v[210:213], v[50:65]
	s_add_i32 m0, s44, s83
	s_lshl_b32 s2, s40, 1
	global_load_lds_dwordx4 v218, s[98:99]
	s_add_i32 s46, s2, s84
	s_mov_b32 m0, s46
	s_add_u32 s98, s98, 0x10000
	s_addc_u32 s99, s99, 0
	global_load_lds_dwordx4 v219, s[100:101]
	s_add_i32 m0, s46, 0x1f80
	v_mfma_f32_32x32x16_bf16 v[34:49], v[158:161], v[206:209], v[34:49]
	global_load_lds_dwordx4 v219, s[100:101] offset:128
	s_add_u32 s100, s100, 0x10000
	s_addc_u32 s101, s101, 0
	v_mfma_f32_32x32x16_bf16 v[50:65], v[154:157], v[130:133], v[50:65]
	v_max_f32_e32 v126, v98, v99
	v_max3_f32 v127, v100, v101, v83
	v_max3_f32 v126, v126, v82, v84
	v_max3_f32 v126, v126, v85, v102
	v_max3_f32 v127, v127, v104, v105
	v_max3_f32 v126, v126, v103, v86
	v_max3_f32 v127, v127, v88, v89
	v_max3_f32 v126, v126, v87, v106
	v_mfma_f32_32x32x16_bf16 v[34:49], v[154:157], v[134:137], v[34:49]
	v_max3_f32 v127, v127, v108, v109
	v_max3_f32 v126, v126, v107, v90
	v_max3_f32 v127, v127, v92, v93
	v_max3_f32 v126, v126, v91, v110
	v_max3_f32 v127, v127, v112, v113
	v_max3_f32 v126, v126, v111, v94
	v_max3_f32 v127, v127, v96, v97
	v_max3_f32 v126, v126, v95, v127
	v_mov_b32_e32 v127, v126
	v_add_f32_e32 v244, v230, v142
	v_add_u32_e32 v130, s45, v228
	v_permlane32_swap_b32_e32 v126, v127
	v_max_f32_e32 v126, v126, v127
	v_cmp_lt_f32_e32 vcc, s87, v126
	s_cbranch_vccnz .LBB0_984
.LBB0_977:
	v_add_u32_e32 v126, s40, v241
	ds_read_b128 v[206:209], v126
	ds_read_b128 v[202:205], v126 offset:512
	ds_read_b128 v[198:201], v126 offset:2048
	ds_read_b128 v[194:197], v126 offset:2560
	s_waitcnt lgkmcnt(4)
	v_mfma_f32_32x32x16_bf16 v[50:65], v[150:153], v[138:141], v[50:65]
	v_exp_f32_e32 v98, v98
	v_exp_f32_e32 v99, v99
	v_exp_f32_e32 v100, v100
	ds_read_b128 v[190:193], v126 offset:4096
	ds_read_b128 v[186:189], v126 offset:4608
	ds_read_b128 v[182:185], v126 offset:6144
	ds_read_b128 v[178:181], v126 offset:6656
	ds_read_b64_tr_b16 v[126:127],v130 offset:3072
	ds_read_b64_tr_b16 v[128:129],v130 offset:3584
	v_mfma_f32_32x32x16_bf16 v[34:49], v[150:153], v[114:117], v[34:49]
	v_exp_f32_e32 v101, v101
	v_exp_f32_e32 v102, v102
	v_exp_f32_e32 v103, v103
	ds_read_b64_tr_b16 v[114:115],v130 offset:0
	ds_read_b64_tr_b16 v[116:117],v130 offset:512
	v_mfma_f32_32x32x16_bf16 v[50:65], v[146:149], v[118:121], v[50:65]
	v_exp_f32_e32 v104, v104
	v_exp_f32_e32 v105, v105
	v_exp_f32_e32 v106, v106
	ds_read_b64_tr_b16 v[118:119],v130 offset:1024
	ds_read_b64_tr_b16 v[120:121],v130 offset:1536
	v_mfma_f32_32x32x16_bf16 v[34:49], v[146:149], v[122:125], v[34:49]
	v_exp_f32_e32 v107, v107
	v_exp_f32_e32 v108, v108
	v_exp_f32_e32 v109, v109
	ds_read_b64_tr_b16 v[122:123],v130 offset:2048
	ds_read_b64_tr_b16 v[124:125],v130 offset:2560
	s_waitcnt lgkmcnt(6)
	v_mfma_f32_32x32x16_bf16 v[18:33], v[146:149], v[126:129], v[18:33]
	v_exp_f32_e32 v110, v110
	v_exp_f32_e32 v111, v111
	v_exp_f32_e32 v112, v112
	ds_read_b64_tr_b16 v[126:127],v130 offset:7168
	ds_read_b64_tr_b16 v[128:129],v130 offset:7680
	s_waitcnt lgkmcnt(6)
	v_mfma_f32_32x32x16_bf16 v[18:33], v[158:161], v[114:117], v[18:33]
	v_exp_f32_e32 v113, v113
	v_exp_f32_e32 v82, v82
	v_exp_f32_e32 v83, v83
	ds_read_b64_tr_b16 v[114:115],v130 offset:4096
	ds_read_b64_tr_b16 v[116:117],v130 offset:4608
	s_waitcnt lgkmcnt(6)
	v_mfma_f32_32x32x16_bf16 v[18:33], v[154:157], v[118:121], v[18:33]
	v_exp_f32_e32 v84, v84
	v_exp_f32_e32 v85, v85
	v_exp_f32_e32 v86, v86
	ds_read_b64_tr_b16 v[118:119],v130 offset:5120
	ds_read_b64_tr_b16 v[120:121],v130 offset:5632
	s_waitcnt lgkmcnt(6)
	v_mfma_f32_32x32x16_bf16 v[18:33], v[150:153], v[122:125], v[18:33]
	v_exp_f32_e32 v87, v87
	v_exp_f32_e32 v88, v88
	v_exp_f32_e32 v89, v89
	ds_read_b64_tr_b16 v[122:123],v130 offset:6144
	ds_read_b64_tr_b16 v[124:125],v130 offset:6656
	s_waitcnt lgkmcnt(6)
	v_mfma_f32_32x32x16_bf16 v[2:17], v[146:149], v[126:129], v[2:17]
	v_exp_f32_e32 v90, v90
	v_exp_f32_e32 v91, v91
	s_waitcnt vmcnt(3) lgkmcnt(0)
	s_barrier
	v_mfma_f32_32x32x16_bf16 v[2:17], v[158:161], v[114:117], v[2:17]
	v_exp_f32_e32 v92, v92
	v_exp_f32_e32 v93, v93
	v_mfma_f32_32x32x16_bf16 v[2:17], v[154:157], v[118:121], v[2:17]
	v_exp_f32_e32 v94, v94
	v_exp_f32_e32 v95, v95
	v_mfma_f32_32x32x16_bf16 v[2:17], v[150:153], v[122:125], v[2:17]
	v_exp_f32_e32 v96, v96
	v_exp_f32_e32 v97, v97
	s_cmp_eq_u32 s3, 0
	s_cbranch_scc1 .LBB0_979
	s_waitcnt lgkmcnt(0)
	s_mov_b32 s3, 0
	v_add_u32_e32 v229, s94, v243
	ds_read_b128 v[114:117], v229 offset:96
	ds_read_b128 v[118:121], v229 offset:64
	ds_read_b128 v[122:125], v229 offset:32
	ds_read_b128 v[126:129], v229
	s_waitcnt lgkmcnt(3)
	v_pk_mul_f32 v[62:63], v[62:63], v[114:115]
	s_waitcnt lgkmcnt(2)
	v_pk_mul_f32 v[58:59], v[58:59], v[118:119]
	s_waitcnt lgkmcnt(1)
	v_pk_mul_f32 v[54:55], v[54:55], v[122:123]
	v_pk_mul_f32 v[64:65], v[64:65], v[116:117]
	v_pk_mul_f32 v[60:61], v[60:61], v[120:121]
	v_pk_mul_f32 v[56:57], v[56:57], v[124:125]
	s_waitcnt lgkmcnt(0)
	v_pk_mul_f32 v[52:53], v[52:53], v[128:129]
	v_pk_mul_f32 v[50:51], v[50:51], v[126:127]
	v_pk_mul_f32 v[46:47], v[46:47], v[114:115]
	v_pk_mul_f32 v[42:43], v[42:43], v[118:119]
	v_pk_mul_f32 v[38:39], v[38:39], v[122:123]
	v_pk_mul_f32 v[48:49], v[48:49], v[116:117]
	v_pk_mul_f32 v[44:45], v[44:45], v[120:121]
	v_pk_mul_f32 v[40:41], v[40:41], v[124:125]
	v_pk_mul_f32 v[36:37], v[36:37], v[128:129]
	v_pk_mul_f32 v[34:35], v[34:35], v[126:127]
	v_pk_mul_f32 v[30:31], v[30:31], v[114:115]
	v_pk_mul_f32 v[26:27], v[26:27], v[118:119]
	v_pk_mul_f32 v[22:23], v[22:23], v[122:123]
	v_pk_mul_f32 v[32:33], v[32:33], v[116:117]
	v_pk_mul_f32 v[28:29], v[28:29], v[120:121]
	v_pk_mul_f32 v[24:25], v[24:25], v[124:125]
	v_pk_mul_f32 v[20:21], v[20:21], v[128:129]
	v_pk_mul_f32 v[18:19], v[18:19], v[126:127]
	v_pk_mul_f32 v[14:15], v[14:15], v[114:115]
	v_pk_mul_f32 v[10:11], v[10:11], v[118:119]
	v_pk_mul_f32 v[6:7], v[6:7], v[122:123]
	v_pk_mul_f32 v[16:17], v[16:17], v[116:117]
	v_pk_mul_f32 v[12:13], v[12:13], v[120:121]
	v_pk_mul_f32 v[8:9], v[8:9], v[124:125]
	v_pk_mul_f32 v[4:5], v[4:5], v[128:129]
	v_pk_mul_f32 v[2:3], v[2:3], v[126:127]

.LBB0_981:
	s_mov_b32 s3, 1
	v_max_f32_e32 v66, v82, v82
	v_max_f32_e32 v82, 0, v66
	v_exp_f32_e64 v83, -v82
	v_add_f32_e32 v240, v240, v82
	v_xor_b32_e32 v66, 0x80000000, v240
	v_mov_b32_e32 v67, v66
	v_mov_b32_e32 v68, v66
	v_mov_b32_e32 v69, v66
	v_mov_b32_e32 v70, v66
	v_mov_b32_e32 v71, v66
	v_mov_b32_e32 v72, v66
	v_mov_b32_e32 v73, v66
	v_mov_b32_e32 v74, v66
	v_mov_b32_e32 v75, v66
	v_mov_b32_e32 v76, v66
	v_mov_b32_e32 v77, v66
	v_mov_b32_e32 v78, v66
	v_mov_b32_e32 v79, v66
	v_mov_b32_e32 v80, v66
	v_mov_b32_e32 v81, v66
	s_and_saveexec_b64 s[66:67], s[0:1]
	ds_write_b32 v237, v83
	s_or_b64 exec, exec, s[66:67]
	v_sub_f32_e32 v145, v145, v82
	v_sub_f32_e32 v144, v144, v82
	v_sub_f32_e32 v143, v143, v82
	v_sub_f32_e32 v142, v142, v82
	v_sub_f32_e32 v141, v141, v82
	v_sub_f32_e32 v140, v140, v82
	v_sub_f32_e32 v139, v139, v82
	v_sub_f32_e32 v138, v138, v82
	v_sub_f32_e32 v137, v137, v82
	v_sub_f32_e32 v136, v136, v82
	v_sub_f32_e32 v135, v135, v82
	v_sub_f32_e32 v134, v134, v82
	v_sub_f32_e32 v133, v133, v82
	v_sub_f32_e32 v132, v132, v82
	v_sub_f32_e32 v131, v131, v82
	v_sub_f32_e32 v130, v130, v82
	v_sub_f32_e32 v129, v129, v82
	v_sub_f32_e32 v128, v128, v82
	v_sub_f32_e32 v127, v127, v82
	v_sub_f32_e32 v126, v126, v82
	v_sub_f32_e32 v125, v125, v82
	v_sub_f32_e32 v124, v124, v82
	v_sub_f32_e32 v123, v123, v82
	v_sub_f32_e32 v122, v122, v82
	v_sub_f32_e32 v121, v121, v82
	v_sub_f32_e32 v120, v120, v82
	v_sub_f32_e32 v119, v119, v82
	v_sub_f32_e32 v118, v118, v82
	v_sub_f32_e32 v117, v117, v82
	v_sub_f32_e32 v116, v116, v82
	v_sub_f32_e32 v115, v115, v82
	v_sub_f32_e32 v114, v114, v82
	v_mul_f32_e32 v230, v230, v83
	s_branch .LBB0_974
.LBB0_984:
	s_mov_b32 s3, 1
	v_max_f32_e32 v66, v126, v126
	v_max_f32_e32 v126, 0, v66
	v_exp_f32_e64 v127, -v126
	v_add_f32_e32 v240, v240, v126
	v_xor_b32_e32 v66, 0x80000000, v240
	v_mov_b32_e32 v67, v66
	v_mov_b32_e32 v68, v66
	v_mov_b32_e32 v69, v66
	v_mov_b32_e32 v70, v66
	v_mov_b32_e32 v71, v66
	v_mov_b32_e32 v72, v66
	v_mov_b32_e32 v73, v66
	v_mov_b32_e32 v74, v66
	v_mov_b32_e32 v75, v66
	v_mov_b32_e32 v76, v66
	v_mov_b32_e32 v77, v66
	v_mov_b32_e32 v78, v66
	v_mov_b32_e32 v79, v66
	v_mov_b32_e32 v80, v66
	v_mov_b32_e32 v81, v66
	s_and_saveexec_b64 s[66:67], s[0:1]
	ds_write_b32 v237, v127
	s_or_b64 exec, exec, s[66:67]
	v_sub_f32_e32 v113, v113, v126
	v_sub_f32_e32 v112, v112, v126
	v_sub_f32_e32 v111, v111, v126
	v_sub_f32_e32 v110, v110, v126
	v_sub_f32_e32 v109, v109, v126
	v_sub_f32_e32 v108, v108, v126
	v_sub_f32_e32 v107, v107, v126
	v_sub_f32_e32 v106, v106, v126
	v_sub_f32_e32 v105, v105, v126
	v_sub_f32_e32 v104, v104, v126
	v_sub_f32_e32 v103, v103, v126
	v_sub_f32_e32 v102, v102, v126
	v_sub_f32_e32 v101, v101, v126
	v_sub_f32_e32 v100, v100, v126
	v_sub_f32_e32 v99, v99, v126
	v_sub_f32_e32 v98, v98, v126
	v_sub_f32_e32 v97, v97, v126
	v_sub_f32_e32 v96, v96, v126
	v_sub_f32_e32 v95, v95, v126
	v_sub_f32_e32 v94, v94, v126
	v_sub_f32_e32 v93, v93, v126
	v_sub_f32_e32 v92, v92, v126
	v_sub_f32_e32 v91, v91, v126
	v_sub_f32_e32 v90, v90, v126
	v_sub_f32_e32 v89, v89, v126
	v_sub_f32_e32 v88, v88, v126
	v_sub_f32_e32 v87, v87, v126
	v_sub_f32_e32 v86, v86, v126
	v_sub_f32_e32 v85, v85, v126
	v_sub_f32_e32 v84, v84, v126
	v_sub_f32_e32 v83, v83, v126
	v_sub_f32_e32 v82, v82, v126
	v_mul_f32_e32 v244, v244, v127
	s_branch .LBB0_977

.LBB0_1077:
	s_and_b32 s1, s41, 0x3fffffc0
	s_cmp_lg_u32 0, -1
	v_lshlrev_b32_e32 v3, 1, v52
	s_cselect_b32 s0, 0, 0
	v_lshlrev_b32_e32 v4, 4, v52
	v_and_b32_e32 v3, 32, v3
	s_add_i32 s3, s0, 0x6000
	v_and_b32_e32 v4, 0xc0, v4
	v_add_u32_e32 v54, s3, v3
	v_lshl_or_b32 v55, v220, 8, v4
	v_add_u32_e32 v3, 0, v3
	v_add3_u32 v242, v3, v53, v55
	v_add3_u32 v237, v54, v53, v55
	v_max3_f32 v53, v34, v35, v18
	v_max3_f32 v54, v36, v37, v19
	s_lshl_b32 s1, s1, 2
	v_max3_f32 v53, v53, v20, v21
	v_max3_f32 v54, v54, v40, v41
	s_add_i32 s39, s1, 0
	v_max3_f32 v53, v53, v38, v39
	v_max3_f32 v54, v54, v24, v25
	s_add_i32 s2, s0, s2
	v_max3_f32 v53, v53, v22, v23
	v_max3_f32 v54, v54, v44, v45
	s_add_i32 s0, s2, 0xa000
	v_max3_f32 v53, v53, v42, v43
	v_max3_f32 v54, v54, v28, v29
	s_add_i32 s2, s2, 0xc000
	v_max3_f32 v53, v53, v26, v27
	v_max3_f32 v54, v54, v48, v49
	s_add_i32 s39, s39, 0x12000
	v_max3_f32 v53, v53, v46, v47
	v_max3_f32 v54, v54, v32, v33
	s_mov_b32 s8, 1
	v_max3_f32 v53, v53, v30, v31
	s_mov_b32 s43, 0
	v_max_f32_e32 v53, v53, v54
	v_mov_b32_e32 v3, v2
	v_mov_b32_e32 v54, v53
	s_nop 1
	v_permlane32_swap_b32_e32 v53, v54
	v_max_f32_e32 v53, v53, v54
	v_mov_b32_e32 v4, v2
	v_add_f32_e32 v240, v225, v53
	v_sub_f32_e32 v18, v18, v53
	v_sub_f32_e32 v19, v19, v53
	v_sub_f32_e32 v34, v34, v53
	v_sub_f32_e32 v35, v35, v53
	v_sub_f32_e32 v36, v36, v53
	s_nop 0
	v_xor_b32_e32 v66, 0x80000000, v240
	v_mov_b32_e32 v67, v66
	v_mov_b32_e32 v68, v66
	v_mov_b32_e32 v69, v66
	v_mov_b32_e32 v70, v66
	v_mov_b32_e32 v71, v66
	v_mov_b32_e32 v72, v66
	v_mov_b32_e32 v73, v66
	v_mov_b32_e32 v74, v66
	v_mov_b32_e32 v75, v66
	v_mov_b32_e32 v76, v66
	v_mov_b32_e32 v77, v66
	v_mov_b32_e32 v78, v66
	v_mov_b32_e32 v79, v66
	v_mov_b32_e32 v80, v66
	v_mov_b32_e32 v81, v66
	s_waitcnt vmcnt(0) lgkmcnt(0)
	s_barrier
	v_exp_f32_e32 v82, v18
	v_exp_f32_e32 v83, v19
	v_lshl_add_u64 v[18:19], v[226:227], 0, s[20:21]
	s_mov_b32 s1, m0
	s_mov_b32 m0, s44
	s_nop 0
	global_load_lds_dwordx4 v[18:19], off
	s_mov_b32 m0, s1
	v_lshl_add_u64 v[18:19], v[50:51], 0, s[10:11]
	s_mov_b32 s1, m0
	s_mov_b32 m0, s0
	s_nop 0
	global_load_lds_dwordx4 v[18:19], off
	s_mov_b32 m0, s1
	s_mov_b64 s[0:1], 0x10080
	v_lshl_add_u64 v[18:19], v[50:51], 0, s[0:1]
	s_mov_b32 s0, m0
	s_mov_b32 m0, s2
	s_nop 0
	global_load_lds_dwordx4 v[18:19], off
	s_mov_b32 m0, s0
	ds_read_b128 v[206:209], v241 offset:8192
	ds_read_b128 v[198:201], v241 offset:8704
	ds_read_b128 v[202:205], v241 offset:10240
	ds_read_b128 v[194:197], v241 offset:10752
	ds_read_b128 v[190:193], v241 offset:12288
	ds_read_b128 v[186:189], v241 offset:12800
	ds_read_b128 v[182:185], v241 offset:14336
	ds_read_b128 v[178:181], v241 offset:14848
	v_sub_f32_e32 v20, v20, v53
	v_sub_f32_e32 v37, v37, v53
	v_sub_f32_e32 v21, v21, v53
	v_sub_f32_e32 v38, v38, v53
	v_sub_f32_e32 v22, v22, v53
	v_sub_f32_e32 v39, v39, v53
	v_sub_f32_e32 v23, v23, v53
	v_sub_f32_e32 v40, v40, v53
	v_sub_f32_e32 v24, v24, v53
	v_sub_f32_e32 v41, v41, v53
	v_sub_f32_e32 v25, v25, v53
	v_sub_f32_e32 v42, v42, v53
	v_sub_f32_e32 v26, v26, v53
	v_sub_f32_e32 v43, v43, v53
	v_sub_f32_e32 v27, v27, v53
	v_sub_f32_e32 v44, v44, v53
	v_sub_f32_e32 v28, v28, v53
	v_sub_f32_e32 v45, v45, v53
	v_sub_f32_e32 v29, v29, v53
	v_sub_f32_e32 v46, v46, v53
	v_sub_f32_e32 v30, v30, v53
	v_sub_f32_e32 v47, v47, v53
	v_sub_f32_e32 v31, v31, v53
	v_sub_f32_e32 v48, v48, v53
	v_sub_f32_e32 v32, v32, v53
	v_sub_f32_e32 v49, v49, v53
	v_sub_f32_e32 v33, v33, v53
	v_exp_f32_e32 v98, v34
	v_exp_f32_e32 v99, v35
	v_exp_f32_e32 v100, v36
	v_exp_f32_e32 v101, v37
	v_exp_f32_e32 v102, v38
	v_exp_f32_e32 v103, v39
	v_exp_f32_e32 v104, v40
	v_exp_f32_e32 v105, v41
	v_exp_f32_e32 v106, v42
	v_exp_f32_e32 v107, v43
	v_exp_f32_e32 v108, v44
	v_exp_f32_e32 v109, v45
	v_exp_f32_e32 v110, v46
	v_exp_f32_e32 v111, v47
	v_exp_f32_e32 v112, v48
	v_exp_f32_e32 v113, v49
	v_exp_f32_e32 v84, v20
	v_exp_f32_e32 v85, v21
	v_exp_f32_e32 v86, v22
	v_exp_f32_e32 v87, v23
	v_exp_f32_e32 v88, v24
	v_exp_f32_e32 v89, v25
	v_exp_f32_e32 v90, v26
	v_exp_f32_e32 v91, v27
	v_exp_f32_e32 v92, v28
	v_exp_f32_e32 v93, v29
	v_exp_f32_e32 v94, v30
	v_exp_f32_e32 v95, v31
	v_exp_f32_e32 v96, v32
	v_exp_f32_e32 v97, v33
	s_waitcnt vmcnt(3) lgkmcnt(0)
	s_barrier
	v_and_b32_e32 v18, 3, v52
	v_mov_b32_e32 v5, v2
	v_mov_b32_e32 v6, v2
	v_mov_b32_e32 v7, v2
	v_mov_b32_e32 v8, v2
	v_mov_b32_e32 v9, v2
	v_mov_b32_e32 v10, v2
	v_mov_b32_e32 v11, v2
	v_mov_b32_e32 v12, v2
	v_mov_b32_e32 v13, v2
	v_mov_b32_e32 v14, v2
	v_mov_b32_e32 v15, v2
	v_mov_b32_e32 v16, v2
	v_mov_b32_e32 v17, v2
	s_cmp_lt_i32 s46, 7
	v_cmp_gt_u32_e64 s[0:1], 32, v223
	v_lshlrev_b32_e32 v243, 4, v220
	v_lshl_add_u32 v238, v234, 2, s39
	v_lshlrev_b32_e32 v224, 4, v18
	s_cbranch_scc1 .LBB0_1093
	s_add_i32 s42, s46, -5
	s_lshl_b64 s[2:3], s[30:31], 1
	s_add_u32 s2, s2, s16
	s_addc_u32 s3, s3, s17
	s_add_u32 s2, s2, s4
	s_addc_u32 s3, s3, s5
	v_lshl_add_u64 v[18:19], s[2:3], 0, v[224:225]
	s_lshl_b32 s2, s41, 8
	s_and_b32 s2, s2, 0xc000
	v_lshl_or_b32 v20, v221, 10, s2
	v_mov_b32_e32 v21, v225
	v_readlane_b32 s52, v254, 6
	v_lshl_add_u64 v[18:19], v[18:19], 0, v[20:21]
	v_readlane_b32 s58, v254, 12
	v_readlane_b32 s59, v254, 13
	v_mov_b64_e32 v[64:65], v[16:17]
	v_mov_b64_e32 v[48:49], v[16:17]
	v_lshl_add_u64 v[214:215], s[58:59], 0, v[18:19]
	v_mov_b64_e32 v[32:33], v[16:17]
	s_movk_i32 s48, 0x2000
	v_add_u32_e32 v228, 0x2000, v237
	s_movk_i32 s43, 0x4000
	s_mov_b32 s2, 0
	v_mov_b32_e32 v244, 0
	s_mov_b64 s[34:35], 0
	v_mov_b64_e32 v[62:63], v[14:15]
	v_mov_b64_e32 v[60:61], v[12:13]
	v_mov_b64_e32 v[58:59], v[10:11]
	v_mov_b64_e32 v[56:57], v[8:9]
	v_mov_b64_e32 v[54:55], v[6:7]
	v_mov_b64_e32 v[52:53], v[4:5]
	v_mov_b64_e32 v[50:51], v[2:3]
	v_mov_b64_e32 v[46:47], v[14:15]
	v_mov_b64_e32 v[44:45], v[12:13]
	v_mov_b64_e32 v[42:43], v[10:11]
	v_mov_b64_e32 v[40:41], v[8:9]
	v_mov_b64_e32 v[38:39], v[6:7]
	v_mov_b64_e32 v[36:37], v[4:5]
	v_mov_b64_e32 v[34:35], v[2:3]
	v_mov_b64_e32 v[30:31], v[14:15]
	v_mov_b64_e32 v[28:29], v[12:13]
	v_mov_b64_e32 v[26:27], v[10:11]
	v_mov_b64_e32 v[24:25], v[8:9]
	v_mov_b64_e32 v[22:23], v[6:7]
	v_mov_b64_e32 v[20:21], v[4:5]
	v_mov_b64_e32 v[18:19], v[2:3]
	v_readlane_b32 s53, v254, 7
	v_readlane_b32 s54, v254, 8
	v_readlane_b32 s55, v254, 9
	v_readlane_b32 s56, v254, 10
	v_readlane_b32 s57, v254, 11
	v_readfirstlane_b32 s98, v226
	v_readfirstlane_b32 s99, v227
	v_readfirstlane_b32 s100, v214
	v_readfirstlane_b32 s101, v215
	s_mov_b32 s3, 0
	v_subrev_u32_e32 v218, s98, v226
	v_subrev_u32_e32 v219, s100, v214
	s_add_u32 s98, s98, s34
	s_addc_u32 s99, s99, s35
	s_add_u32 s98, s98, s22
	s_addc_u32 s99, s99, s23
	s_add_u32 s100, s100, s34
	s_addc_u32 s101, s101, s35
	s_add_u32 s100, s100, s24
	s_addc_u32 s101, s101, s25
.LBB0_1079:
	s_lshl_b32 s40, s2, 1
	v_add_u32_e32 v216, s40, v242
	ds_read_b64_tr_b16 v[210:211], v216 offset:24576
	ds_read_b64_tr_b16 v[212:213], v216 offset:25088
	v_mfma_f32_32x32x16_bf16 v[130:145], v[206:209], v[174:177], v[66:81]
	v_add_f32_e32 v114, v98, v99
	v_add_f32_e32 v114, v100, v114
	v_add_f32_e32 v114, v101, v114
	v_add_f32_e32 v114, v102, v114
	v_add_f32_e32 v114, v103, v114
	v_cvt_pk_bf16_f32 v166, v98, v99
	v_cvt_pk_bf16_f32 v167, v100, v101
	ds_read_b64_tr_b16 v[206:207], v216 offset:28672
	ds_read_b64_tr_b16 v[208:209], v216 offset:29184
	v_add_f32_e32 v98, v104, v114
	v_mfma_f32_32x32x16_bf16 v[114:129], v[198:201], v[174:177], v[66:81]
	v_add_f32_e32 v98, v105, v98
	v_add_f32_e32 v98, v106, v98
	v_add_f32_e32 v154, v107, v98
	v_cvt_pk_bf16_f32 v168, v102, v103
	v_cvt_pk_bf16_f32 v169, v104, v105
	ds_read_b64_tr_b16 v[98:99], v216 offset:25600
	ds_read_b64_tr_b16 v[100:101], v216 offset:26112
	v_mfma_f32_32x32x16_bf16 v[130:145], v[202:205], v[170:173], v[130:145]
	v_add_f32_e32 v102, v108, v154
	v_add_f32_e32 v102, v109, v102
	v_add_f32_e32 v102, v110, v102
	v_add_f32_e32 v154, v111, v102
	v_cvt_pk_bf16_f32 v162, v106, v107
	v_cvt_pk_bf16_f32 v163, v108, v109
	ds_read_b64_tr_b16 v[102:103], v216 offset:29696
	ds_read_b64_tr_b16 v[104:105], v216 offset:30208
	v_mfma_f32_32x32x16_bf16 v[114:129], v[194:197], v[170:173], v[114:129]
	v_add_f32_e32 v106, v112, v154
	v_add_f32_e32 v106, v113, v106
	v_add_f32_e32 v106, v82, v106
	v_add_f32_e32 v154, v83, v106
	v_cvt_pk_bf16_f32 v164, v110, v111
	v_cvt_pk_bf16_f32 v165, v112, v113
	ds_read_b64_tr_b16 v[106:107], v216 offset:26624
	ds_read_b64_tr_b16 v[108:109], v216 offset:27136
	v_mfma_f32_32x32x16_bf16 v[130:145], v[190:193], v[150:153], v[130:145]
	v_add_f32_e32 v110, v84, v154
	v_add_f32_e32 v110, v85, v110
	v_add_f32_e32 v110, v86, v110
	v_add_f32_e32 v154, v87, v110
	v_cvt_pk_bf16_f32 v158, v82, v83
	v_cvt_pk_bf16_f32 v159, v84, v85
	ds_read_b64_tr_b16 v[110:111], v216 offset:30720
	ds_read_b64_tr_b16 v[112:113], v216 offset:31232
	v_mfma_f32_32x32x16_bf16 v[114:129], v[186:189], v[150:153], v[114:129]
	v_add_f32_e32 v82, v88, v154
	v_add_f32_e32 v82, v89, v82
	v_add_f32_e32 v82, v90, v82
	v_add_f32_e32 v82, v91, v82
	v_cvt_pk_bf16_f32 v160, v86, v87
	v_cvt_pk_bf16_f32 v161, v88, v89
	ds_read_b64_tr_b16 v[86:87], v216 offset:27648
	ds_read_b64_tr_b16 v[88:89], v216 offset:28160
	v_mfma_f32_32x32x16_bf16 v[130:145], v[182:185], v[146:149], v[130:145]
	v_add_f32_e32 v82, v92, v82
	v_add_f32_e32 v82, v93, v82
	v_add_f32_e32 v82, v94, v82
	v_add_f32_e32 v82, v95, v82
	v_cvt_pk_bf16_f32 v154, v90, v91
	v_cvt_pk_bf16_f32 v155, v92, v93
	ds_read_b64_tr_b16 v[90:91], v216 offset:31744
	ds_read_b64_tr_b16 v[92:93], v216 offset:32256
	v_mfma_f32_32x32x16_bf16 v[114:129], v[178:181], v[146:149], v[114:129]
	v_add_f32_e32 v82, v96, v82
	v_add_f32_e32 v82, v97, v82
	v_add_f32_e32 v230, v244, v82
	v_cvt_pk_bf16_f32 v156, v94, v95
	v_cvt_pk_bf16_f32 v157, v96, v97
	s_waitcnt lgkmcnt(8)
	v_mfma_f32_32x32x16_bf16 v[50:65], v[166:169], v[210:213], v[50:65]
	s_add_i32 m0, s48, s44
	s_lshl_b32 s2, s43, 1
	global_load_lds_dwordx4 v218, s[98:99]
	s_add_i32 m0, s2, s45
	s_add_u32 s98, s98, 0x10000
	s_addc_u32 s99, s99, 0
	global_load_lds_dwordx4 v219, s[100:101]
	s_addk_i32 m0, 0x1f80
	v_mfma_f32_32x32x16_bf16 v[34:49], v[166:169], v[206:209], v[34:49]
	global_load_lds_dwordx4 v219, s[100:101] offset:128
	s_add_u32 s100, s100, 0x10000
	s_addc_u32 s101, s101, 0
	v_mfma_f32_32x32x16_bf16 v[50:65], v[162:165], v[98:101], v[50:65]
	v_max_f32_e32 v82, v130, v131
	v_max3_f32 v83, v132, v133, v115
	v_max3_f32 v82, v82, v114, v116
	v_max3_f32 v82, v82, v117, v134
	v_max3_f32 v83, v83, v136, v137
	v_max3_f32 v82, v82, v135, v118
	v_max3_f32 v83, v83, v120, v121
	v_max3_f32 v82, v82, v119, v138
	v_mfma_f32_32x32x16_bf16 v[34:49], v[162:165], v[102:105], v[34:49]
	v_max3_f32 v83, v83, v140, v141
	v_max3_f32 v82, v82, v139, v122
	v_max3_f32 v83, v83, v124, v125
	v_max3_f32 v82, v82, v123, v142
	v_max3_f32 v83, v83, v144, v145
	v_max3_f32 v82, v82, v143, v126
	v_max3_f32 v83, v83, v128, v129
	v_max3_f32 v82, v82, v127, v83
	v_mov_b32_e32 v83, v82
	v_add_u32_e32 v94, s43, v241
	v_add_u32_e32 v102, s40, v228
	v_permlane32_swap_b32_e32 v82, v83
	v_max_f32_e32 v82, v82, v83
	v_cmp_lt_f32_e32 vcc, s15, v82
	s_cbranch_vccnz .LBB0_1087
.LBB0_1080:
	ds_read_b128 v[82:85], v94
	ds_read_b128 v[198:201], v94 offset:512
	ds_read_b128 v[202:205], v94 offset:2048
	ds_read_b128 v[194:197], v94 offset:2560
	s_waitcnt lgkmcnt(4)
	v_mfma_f32_32x32x16_bf16 v[50:65], v[158:161], v[106:109], v[50:65]
	v_exp_f32_e32 v130, v130
	v_exp_f32_e32 v131, v131
	v_exp_f32_e32 v132, v132
	ds_read_b128 v[190:193], v94 offset:4096
	ds_read_b128 v[186:189], v94 offset:4608
	ds_read_b128 v[182:185], v94 offset:6144
	ds_read_b128 v[178:181], v94 offset:6656
	ds_read_b64_tr_b16 v[98:99],v102 offset:3072
	ds_read_b64_tr_b16 v[100:101],v102 offset:3584
	ds_read_b64_tr_b16 v[94:95],v102 offset:2048
	ds_read_b64_tr_b16 v[96:97],v102 offset:2560
	v_mfma_f32_32x32x16_bf16 v[34:49], v[158:161], v[110:113], v[34:49]
	v_exp_f32_e32 v133, v133
	v_exp_f32_e32 v134, v134
	v_exp_f32_e32 v135, v135
	v_mfma_f32_32x32x16_bf16 v[50:65], v[154:157], v[86:89], v[50:65]
	v_exp_f32_e32 v136, v136
	v_exp_f32_e32 v137, v137
	v_exp_f32_e32 v138, v138
	ds_read_b64_tr_b16 v[86:87],v102 offset:0
	ds_read_b64_tr_b16 v[88:89],v102 offset:512
	v_mfma_f32_32x32x16_bf16 v[34:49], v[154:157], v[90:93], v[34:49]
	v_exp_f32_e32 v139, v139
	v_exp_f32_e32 v140, v140
	v_exp_f32_e32 v141, v141
	ds_read_b64_tr_b16 v[90:91],v102 offset:1024
	ds_read_b64_tr_b16 v[92:93],v102 offset:1536
	s_waitcnt lgkmcnt(6)
	v_mfma_f32_32x32x16_bf16 v[18:33], v[154:157], v[98:101], v[18:33]
	v_exp_f32_e32 v142, v142
	v_exp_f32_e32 v143, v143
	v_exp_f32_e32 v144, v144
	ds_read_b64_tr_b16 v[98:99],v102 offset:7168
	ds_read_b64_tr_b16 v[100:101],v102 offset:7680
	s_waitcnt lgkmcnt(6)
	v_mfma_f32_32x32x16_bf16 v[18:33], v[158:161], v[94:97], v[18:33]
	v_exp_f32_e32 v145, v145
	v_exp_f32_e32 v114, v114
	v_exp_f32_e32 v115, v115
	ds_read_b64_tr_b16 v[94:95],v102 offset:6144
	ds_read_b64_tr_b16 v[96:97],v102 offset:6656
	s_waitcnt lgkmcnt(6)
	v_mfma_f32_32x32x16_bf16 v[18:33], v[166:169], v[86:89], v[18:33]
	v_exp_f32_e32 v116, v116
	v_exp_f32_e32 v117, v117
	v_exp_f32_e32 v118, v118
	ds_read_b64_tr_b16 v[86:87],v102 offset:4096
	ds_read_b64_tr_b16 v[88:89],v102 offset:4608
	s_waitcnt lgkmcnt(6)
	v_mfma_f32_32x32x16_bf16 v[18:33], v[162:165], v[90:93], v[18:33]
	v_exp_f32_e32 v119, v119
	v_exp_f32_e32 v120, v120
	v_exp_f32_e32 v121, v121
	ds_read_b64_tr_b16 v[90:91],v102 offset:5120
	ds_read_b64_tr_b16 v[92:93],v102 offset:5632
	s_waitcnt lgkmcnt(6)
	v_mfma_f32_32x32x16_bf16 v[2:17], v[154:157], v[98:101], v[2:17]
	v_exp_f32_e32 v122, v122
	v_exp_f32_e32 v123, v123
	s_waitcnt vmcnt(3) lgkmcnt(0)
	s_barrier
	v_mfma_f32_32x32x16_bf16 v[2:17], v[158:161], v[94:97], v[2:17]
	v_exp_f32_e32 v124, v124
	v_exp_f32_e32 v125, v125
	v_mfma_f32_32x32x16_bf16 v[2:17], v[166:169], v[86:89], v[2:17]
	v_exp_f32_e32 v126, v126
	v_exp_f32_e32 v127, v127
	v_mfma_f32_32x32x16_bf16 v[2:17], v[162:165], v[90:93], v[2:17]
	v_exp_f32_e32 v128, v128
	v_exp_f32_e32 v129, v129
	s_cmp_eq_u32 s3, 0
	s_cbranch_scc1 .LBB0_1082
	s_waitcnt lgkmcnt(0)
	s_mov_b32 s3, 0
	v_add_u32_e32 v229, s39, v243
	ds_read_b128 v[86:89], v229 offset:96
	ds_read_b128 v[90:93], v229 offset:64
	ds_read_b128 v[94:97], v229 offset:32
	ds_read_b128 v[98:101], v229
	s_waitcnt lgkmcnt(3)
	v_pk_mul_f32 v[62:63], v[62:63], v[86:87]
	s_waitcnt lgkmcnt(2)
	v_pk_mul_f32 v[58:59], v[58:59], v[90:91]
	s_waitcnt lgkmcnt(1)
	v_pk_mul_f32 v[54:55], v[54:55], v[94:95]
	v_pk_mul_f32 v[64:65], v[64:65], v[88:89]
	v_pk_mul_f32 v[60:61], v[60:61], v[92:93]
	v_pk_mul_f32 v[56:57], v[56:57], v[96:97]
	s_waitcnt lgkmcnt(0)
	v_pk_mul_f32 v[52:53], v[52:53], v[100:101]
	v_pk_mul_f32 v[50:51], v[50:51], v[98:99]
	v_pk_mul_f32 v[46:47], v[46:47], v[86:87]
	v_pk_mul_f32 v[42:43], v[42:43], v[90:91]
	v_pk_mul_f32 v[38:39], v[38:39], v[94:95]
	v_pk_mul_f32 v[48:49], v[48:49], v[88:89]
	v_pk_mul_f32 v[44:45], v[44:45], v[92:93]
	v_pk_mul_f32 v[40:41], v[40:41], v[96:97]
	v_pk_mul_f32 v[36:37], v[36:37], v[100:101]
	v_pk_mul_f32 v[34:35], v[34:35], v[98:99]
	v_pk_mul_f32 v[30:31], v[30:31], v[86:87]
	v_pk_mul_f32 v[26:27], v[26:27], v[90:91]
	v_pk_mul_f32 v[22:23], v[22:23], v[94:95]
	v_pk_mul_f32 v[32:33], v[32:33], v[88:89]
	v_pk_mul_f32 v[28:29], v[28:29], v[92:93]
	v_pk_mul_f32 v[24:25], v[24:25], v[96:97]
	v_pk_mul_f32 v[20:21], v[20:21], v[100:101]
	v_pk_mul_f32 v[18:19], v[18:19], v[98:99]
	v_pk_mul_f32 v[14:15], v[14:15], v[86:87]
	v_pk_mul_f32 v[10:11], v[10:11], v[90:91]
	v_pk_mul_f32 v[6:7], v[6:7], v[94:95]
	v_pk_mul_f32 v[16:17], v[16:17], v[88:89]
	v_pk_mul_f32 v[12:13], v[12:13], v[92:93]
	v_pk_mul_f32 v[8:9], v[8:9], v[96:97]
	v_pk_mul_f32 v[4:5], v[4:5], v[100:101]
	v_pk_mul_f32 v[2:3], v[2:3], v[98:99]
.LBB0_1082:
	s_add_i32 s2, s43, 0x2000
	s_cmpk_lg_i32 s43, 0x4000
	s_cselect_b32 s40, s2, 0
	s_lshl_b32 s47, s48, 1
	v_add_u32_e32 v231, s47, v242
	ds_read_b64_tr_b16 v[210:211], v231 offset:24576
	ds_read_b64_tr_b16 v[212:213], v231 offset:25088
	v_mfma_f32_32x32x16_bf16 v[98:113], v[82:85], v[174:177], v[66:81]
	v_add_f32_e32 v86, v130, v131
	v_add_f32_e32 v86, v132, v86
	v_add_f32_e32 v86, v133, v86
	v_add_f32_e32 v86, v134, v86
	v_add_f32_e32 v86, v135, v86
	v_cvt_pk_bf16_f32 v166, v130, v131
	v_cvt_pk_bf16_f32 v167, v132, v133
	ds_read_b64_tr_b16 v[206:207], v231 offset:28672
	ds_read_b64_tr_b16 v[208:209], v231 offset:29184
	v_add_f32_e32 v82, v136, v86
	v_add_f32_e32 v82, v137, v82
	v_add_f32_e32 v82, v138, v82
	v_add_f32_e32 v154, v139, v82
	v_mfma_f32_32x32x16_bf16 v[82:97], v[198:201], v[174:177], v[66:81]
	v_cvt_pk_bf16_f32 v168, v134, v135
	v_cvt_pk_bf16_f32 v169, v136, v137
	ds_read_b64_tr_b16 v[130:131], v231 offset:25600
	ds_read_b64_tr_b16 v[132:133], v231 offset:26112
	v_mfma_f32_32x32x16_bf16 v[98:113], v[202:205], v[170:173], v[98:113]
	v_add_f32_e32 v134, v140, v154
	v_add_f32_e32 v134, v141, v134
	v_add_f32_e32 v134, v142, v134
	v_add_f32_e32 v154, v143, v134
	v_cvt_pk_bf16_f32 v162, v138, v139
	v_cvt_pk_bf16_f32 v163, v140, v141
	ds_read_b64_tr_b16 v[134:135], v231 offset:29696
	ds_read_b64_tr_b16 v[136:137], v231 offset:30208
	v_mfma_f32_32x32x16_bf16 v[82:97], v[194:197], v[170:173], v[82:97]
	v_add_f32_e32 v138, v144, v154
	v_add_f32_e32 v138, v145, v138
	v_add_f32_e32 v138, v114, v138
	v_add_f32_e32 v154, v115, v138
	v_cvt_pk_bf16_f32 v164, v142, v143
	v_cvt_pk_bf16_f32 v165, v144, v145
	ds_read_b64_tr_b16 v[138:139], v231 offset:26624
	ds_read_b64_tr_b16 v[140:141], v231 offset:27136
	v_mfma_f32_32x32x16_bf16 v[98:113], v[190:193], v[150:153], v[98:113]
	v_add_f32_e32 v142, v116, v154
	v_add_f32_e32 v142, v117, v142
	v_add_f32_e32 v142, v118, v142
	v_add_f32_e32 v142, v119, v142
	v_cvt_pk_bf16_f32 v158, v114, v115
	v_cvt_pk_bf16_f32 v159, v116, v117
	ds_read_b64_tr_b16 v[114:115], v231 offset:30720
	ds_read_b64_tr_b16 v[116:117], v231 offset:31232
	v_mfma_f32_32x32x16_bf16 v[82:97], v[186:189], v[150:153], v[82:97]
	v_add_f32_e32 v142, v120, v142
	v_add_f32_e32 v142, v121, v142
	v_add_f32_e32 v142, v122, v142
	v_add_f32_e32 v142, v123, v142
	v_cvt_pk_bf16_f32 v160, v118, v119
	v_cvt_pk_bf16_f32 v161, v120, v121
	ds_read_b64_tr_b16 v[118:119], v231 offset:27648
	ds_read_b64_tr_b16 v[120:121], v231 offset:28160
	v_mfma_f32_32x32x16_bf16 v[98:113], v[182:185], v[146:149], v[98:113]
	v_add_f32_e32 v142, v124, v142
	v_add_f32_e32 v142, v125, v142
	v_add_f32_e32 v142, v126, v142
	v_add_f32_e32 v142, v127, v142
	v_cvt_pk_bf16_f32 v154, v122, v123
	v_cvt_pk_bf16_f32 v155, v124, v125
	ds_read_b64_tr_b16 v[122:123], v231 offset:31744
	ds_read_b64_tr_b16 v[124:125], v231 offset:32256
	v_mfma_f32_32x32x16_bf16 v[82:97], v[178:181], v[146:149], v[82:97]
	v_add_f32_e32 v142, v128, v142
	v_add_f32_e32 v142, v129, v142
	v_cvt_pk_bf16_f32 v156, v126, v127
	v_cvt_pk_bf16_f32 v157, v128, v129
	s_waitcnt lgkmcnt(8)
	v_mfma_f32_32x32x16_bf16 v[50:65], v[166:169], v[210:213], v[50:65]
	s_add_i32 m0, s43, s44
	s_lshl_b32 s2, s40, 1
	global_load_lds_dwordx4 v218, s[98:99]
	s_add_i32 s36, s2, s45
	s_mov_b32 m0, s36
	s_add_u32 s98, s98, 0x10000
	s_addc_u32 s99, s99, 0
	global_load_lds_dwordx4 v219, s[100:101]
	s_add_i32 m0, s36, 0x1f80
	v_mfma_f32_32x32x16_bf16 v[34:49], v[166:169], v[206:209], v[34:49]
	global_load_lds_dwordx4 v219, s[100:101] offset:128
	s_add_u32 s100, s100, 0x10000
	s_addc_u32 s101, s101, 0
	v_mfma_f32_32x32x16_bf16 v[50:65], v[162:165], v[130:133], v[50:65]
	v_max_f32_e32 v126, v98, v99
	v_max3_f32 v127, v100, v101, v83
	v_max3_f32 v126, v126, v82, v84
	v_max3_f32 v126, v126, v85, v102
	v_max3_f32 v127, v127, v104, v105
	v_max3_f32 v126, v126, v103, v86
	v_max3_f32 v127, v127, v88, v89
	v_max3_f32 v126, v126, v87, v106
	v_mfma_f32_32x32x16_bf16 v[34:49], v[162:165], v[134:137], v[34:49]
	v_max3_f32 v127, v127, v108, v109
	v_max3_f32 v126, v126, v107, v90
	v_max3_f32 v127, v127, v92, v93
	v_max3_f32 v126, v126, v91, v110
	v_max3_f32 v127, v127, v112, v113
	v_max3_f32 v126, v126, v111, v94
	v_max3_f32 v127, v127, v96, v97
	v_max3_f32 v126, v126, v95, v127
	v_mov_b32_e32 v127, v126
	v_add_f32_e32 v244, v230, v142
	v_add_u32_e32 v130, s47, v228
	v_permlane32_swap_b32_e32 v126, v127
	v_max_f32_e32 v126, v126, v127
	v_cmp_lt_f32_e32 vcc, s15, v126
	s_cbranch_vccnz .LBB0_1090
.LBB0_1083:
	v_add_u32_e32 v126, s40, v241
	ds_read_b128 v[206:209], v126
	ds_read_b128 v[198:201], v126 offset:512
	ds_read_b128 v[202:205], v126 offset:2048
	ds_read_b128 v[194:197], v126 offset:2560
	s_waitcnt lgkmcnt(4)
	v_mfma_f32_32x32x16_bf16 v[50:65], v[158:161], v[138:141], v[50:65]
	v_exp_f32_e32 v98, v98
	v_exp_f32_e32 v99, v99
	v_exp_f32_e32 v100, v100
	ds_read_b128 v[190:193], v126 offset:4096
	ds_read_b128 v[186:189], v126 offset:4608
	ds_read_b128 v[182:185], v126 offset:6144
	ds_read_b128 v[178:181], v126 offset:6656
	ds_read_b64_tr_b16 v[126:127],v130 offset:3072
	ds_read_b64_tr_b16 v[128:129],v130 offset:3584
	v_mfma_f32_32x32x16_bf16 v[34:49], v[158:161], v[114:117], v[34:49]
	v_exp_f32_e32 v101, v101
	v_exp_f32_e32 v102, v102
	v_exp_f32_e32 v103, v103
	ds_read_b64_tr_b16 v[114:115],v130 offset:0
	ds_read_b64_tr_b16 v[116:117],v130 offset:512
	v_mfma_f32_32x32x16_bf16 v[50:65], v[154:157], v[118:121], v[50:65]
	v_exp_f32_e32 v104, v104
	v_exp_f32_e32 v105, v105
	v_exp_f32_e32 v106, v106
	ds_read_b64_tr_b16 v[118:119],v130 offset:1024
	ds_read_b64_tr_b16 v[120:121],v130 offset:1536
	v_mfma_f32_32x32x16_bf16 v[34:49], v[154:157], v[122:125], v[34:49]
	v_exp_f32_e32 v107, v107
	v_exp_f32_e32 v108, v108
	v_exp_f32_e32 v109, v109
	ds_read_b64_tr_b16 v[122:123],v130 offset:2048
	ds_read_b64_tr_b16 v[124:125],v130 offset:2560
	s_waitcnt lgkmcnt(6)
	v_mfma_f32_32x32x16_bf16 v[18:33], v[154:157], v[126:129], v[18:33]
	v_exp_f32_e32 v110, v110
	v_exp_f32_e32 v111, v111
	v_exp_f32_e32 v112, v112
	ds_read_b64_tr_b16 v[126:127],v130 offset:7168
	ds_read_b64_tr_b16 v[128:129],v130 offset:7680
	s_waitcnt lgkmcnt(6)
	v_mfma_f32_32x32x16_bf16 v[18:33], v[166:169], v[114:117], v[18:33]
	v_exp_f32_e32 v113, v113
	v_exp_f32_e32 v82, v82
	v_exp_f32_e32 v83, v83
	ds_read_b64_tr_b16 v[114:115],v130 offset:4096
	ds_read_b64_tr_b16 v[116:117],v130 offset:4608
	s_waitcnt lgkmcnt(6)
	v_mfma_f32_32x32x16_bf16 v[18:33], v[162:165], v[118:121], v[18:33]
	v_exp_f32_e32 v84, v84
	v_exp_f32_e32 v85, v85
	v_exp_f32_e32 v86, v86
	ds_read_b64_tr_b16 v[118:119],v130 offset:5120
	ds_read_b64_tr_b16 v[120:121],v130 offset:5632
	s_waitcnt lgkmcnt(6)
	v_mfma_f32_32x32x16_bf16 v[18:33], v[158:161], v[122:125], v[18:33]
	v_exp_f32_e32 v87, v87
	v_exp_f32_e32 v88, v88
	v_exp_f32_e32 v89, v89
	ds_read_b64_tr_b16 v[122:123],v130 offset:6144
	ds_read_b64_tr_b16 v[124:125],v130 offset:6656
	s_waitcnt lgkmcnt(6)
	v_mfma_f32_32x32x16_bf16 v[2:17], v[154:157], v[126:129], v[2:17]
	v_exp_f32_e32 v90, v90
	v_exp_f32_e32 v91, v91
	s_waitcnt vmcnt(3) lgkmcnt(0)
	s_barrier
	v_mfma_f32_32x32x16_bf16 v[2:17], v[166:169], v[114:117], v[2:17]
	v_exp_f32_e32 v92, v92
	v_exp_f32_e32 v93, v93
	v_mfma_f32_32x32x16_bf16 v[2:17], v[162:165], v[118:121], v[2:17]
	v_exp_f32_e32 v94, v94
	v_exp_f32_e32 v95, v95
	v_mfma_f32_32x32x16_bf16 v[2:17], v[158:161], v[122:125], v[2:17]
	v_exp_f32_e32 v96, v96
	v_exp_f32_e32 v97, v97
	s_cmp_eq_u32 s3, 0
	s_cbranch_scc1 .LBB0_1085
	s_waitcnt lgkmcnt(0)
	s_mov_b32 s3, 0
	v_add_u32_e32 v229, s39, v243
	ds_read_b128 v[114:117], v229 offset:96
	ds_read_b128 v[118:121], v229 offset:64
	ds_read_b128 v[122:125], v229 offset:32
	ds_read_b128 v[126:129], v229
	s_waitcnt lgkmcnt(3)
	v_pk_mul_f32 v[62:63], v[62:63], v[114:115]
	s_waitcnt lgkmcnt(2)
	v_pk_mul_f32 v[58:59], v[58:59], v[118:119]
	s_waitcnt lgkmcnt(1)
	v_pk_mul_f32 v[54:55], v[54:55], v[122:123]
	v_pk_mul_f32 v[64:65], v[64:65], v[116:117]
	v_pk_mul_f32 v[60:61], v[60:61], v[120:121]
	v_pk_mul_f32 v[56:57], v[56:57], v[124:125]
	s_waitcnt lgkmcnt(0)
	v_pk_mul_f32 v[52:53], v[52:53], v[128:129]
	v_pk_mul_f32 v[50:51], v[50:51], v[126:127]
	v_pk_mul_f32 v[46:47], v[46:47], v[114:115]
	v_pk_mul_f32 v[42:43], v[42:43], v[118:119]
	v_pk_mul_f32 v[38:39], v[38:39], v[122:123]
	v_pk_mul_f32 v[48:49], v[48:49], v[116:117]
	v_pk_mul_f32 v[44:45], v[44:45], v[120:121]
	v_pk_mul_f32 v[40:41], v[40:41], v[124:125]
	v_pk_mul_f32 v[36:37], v[36:37], v[128:129]
	v_pk_mul_f32 v[34:35], v[34:35], v[126:127]
	v_pk_mul_f32 v[30:31], v[30:31], v[114:115]
	v_pk_mul_f32 v[26:27], v[26:27], v[118:119]
	v_pk_mul_f32 v[22:23], v[22:23], v[122:123]
	v_pk_mul_f32 v[32:33], v[32:33], v[116:117]
	v_pk_mul_f32 v[28:29], v[28:29], v[120:121]
	v_pk_mul_f32 v[24:25], v[24:25], v[124:125]
	v_pk_mul_f32 v[20:21], v[20:21], v[128:129]
	v_pk_mul_f32 v[18:19], v[18:19], v[126:127]
	v_pk_mul_f32 v[14:15], v[14:15], v[114:115]
	v_pk_mul_f32 v[10:11], v[10:11], v[118:119]
	v_pk_mul_f32 v[6:7], v[6:7], v[122:123]
	v_pk_mul_f32 v[16:17], v[16:17], v[116:117]
	v_pk_mul_f32 v[12:13], v[12:13], v[120:121]
	v_pk_mul_f32 v[8:9], v[8:9], v[124:125]
	v_pk_mul_f32 v[4:5], v[4:5], v[128:129]
	v_pk_mul_f32 v[2:3], v[2:3], v[126:127]

.LBB0_1087:
	s_mov_b32 s3, 1
	v_max_f32_e32 v66, v82, v82
	v_max_f32_e32 v82, 0, v66
	v_exp_f32_e64 v83, -v82
	v_add_f32_e32 v240, v240, v82
	v_xor_b32_e32 v66, 0x80000000, v240
	v_mov_b32_e32 v67, v66
	v_mov_b32_e32 v68, v66
	v_mov_b32_e32 v69, v66
	v_mov_b32_e32 v70, v66
	v_mov_b32_e32 v71, v66
	v_mov_b32_e32 v72, v66
	v_mov_b32_e32 v73, v66
	v_mov_b32_e32 v74, v66
	v_mov_b32_e32 v75, v66
	v_mov_b32_e32 v76, v66
	v_mov_b32_e32 v77, v66
	v_mov_b32_e32 v78, v66
	v_mov_b32_e32 v79, v66
	v_mov_b32_e32 v80, v66
	v_mov_b32_e32 v81, v66
	s_and_saveexec_b64 s[36:37], s[0:1]
	ds_write_b32 v238, v83
	s_or_b64 exec, exec, s[36:37]
	v_sub_f32_e32 v145, v145, v82
	v_sub_f32_e32 v144, v144, v82
	v_sub_f32_e32 v143, v143, v82
	v_sub_f32_e32 v142, v142, v82
	v_sub_f32_e32 v141, v141, v82
	v_sub_f32_e32 v140, v140, v82
	v_sub_f32_e32 v139, v139, v82
	v_sub_f32_e32 v138, v138, v82
	v_sub_f32_e32 v137, v137, v82
	v_sub_f32_e32 v136, v136, v82
	v_sub_f32_e32 v135, v135, v82
	v_sub_f32_e32 v134, v134, v82
	v_sub_f32_e32 v133, v133, v82
	v_sub_f32_e32 v132, v132, v82
	v_sub_f32_e32 v131, v131, v82
	v_sub_f32_e32 v130, v130, v82
	v_sub_f32_e32 v129, v129, v82
	v_sub_f32_e32 v128, v128, v82
	v_sub_f32_e32 v127, v127, v82
	v_sub_f32_e32 v126, v126, v82
	v_sub_f32_e32 v125, v125, v82
	v_sub_f32_e32 v124, v124, v82
	v_sub_f32_e32 v123, v123, v82
	v_sub_f32_e32 v122, v122, v82
	v_sub_f32_e32 v121, v121, v82
	v_sub_f32_e32 v120, v120, v82
	v_sub_f32_e32 v119, v119, v82
	v_sub_f32_e32 v118, v118, v82
	v_sub_f32_e32 v117, v117, v82
	v_sub_f32_e32 v116, v116, v82
	v_sub_f32_e32 v115, v115, v82
	v_sub_f32_e32 v114, v114, v82
	v_mul_f32_e32 v230, v230, v83
	s_branch .LBB0_1080
.LBB0_1090:
	s_mov_b32 s3, 1
	v_max_f32_e32 v66, v126, v126
	v_max_f32_e32 v126, 0, v66
	v_exp_f32_e64 v127, -v126
	v_add_f32_e32 v240, v240, v126
	v_xor_b32_e32 v66, 0x80000000, v240
	v_mov_b32_e32 v67, v66
	v_mov_b32_e32 v68, v66
	v_mov_b32_e32 v69, v66
	v_mov_b32_e32 v70, v66
	v_mov_b32_e32 v71, v66
	v_mov_b32_e32 v72, v66
	v_mov_b32_e32 v73, v66
	v_mov_b32_e32 v74, v66
	v_mov_b32_e32 v75, v66
	v_mov_b32_e32 v76, v66
	v_mov_b32_e32 v77, v66
	v_mov_b32_e32 v78, v66
	v_mov_b32_e32 v79, v66
	v_mov_b32_e32 v80, v66
	v_mov_b32_e32 v81, v66
	s_and_saveexec_b64 s[36:37], s[0:1]
	ds_write_b32 v238, v127
	s_or_b64 exec, exec, s[36:37]
	v_sub_f32_e32 v113, v113, v126
	v_sub_f32_e32 v112, v112, v126
	v_sub_f32_e32 v111, v111, v126
	v_sub_f32_e32 v110, v110, v126
	v_sub_f32_e32 v109, v109, v126
	v_sub_f32_e32 v108, v108, v126
	v_sub_f32_e32 v107, v107, v126
	v_sub_f32_e32 v106, v106, v126
	v_sub_f32_e32 v105, v105, v126
	v_sub_f32_e32 v104, v104, v126
	v_sub_f32_e32 v103, v103, v126
	v_sub_f32_e32 v102, v102, v126
	v_sub_f32_e32 v101, v101, v126
	v_sub_f32_e32 v100, v100, v126
	v_sub_f32_e32 v99, v99, v126
	v_sub_f32_e32 v98, v98, v126
	v_sub_f32_e32 v97, v97, v126
	v_sub_f32_e32 v96, v96, v126
	v_sub_f32_e32 v95, v95, v126
	v_sub_f32_e32 v94, v94, v126
	v_sub_f32_e32 v93, v93, v126
	v_sub_f32_e32 v92, v92, v126
	v_sub_f32_e32 v91, v91, v126
	v_sub_f32_e32 v90, v90, v126
	v_sub_f32_e32 v89, v89, v126
	v_sub_f32_e32 v88, v88, v126
	v_sub_f32_e32 v87, v87, v126
	v_sub_f32_e32 v86, v86, v126
	v_sub_f32_e32 v85, v85, v126
	v_sub_f32_e32 v84, v84, v126
	v_sub_f32_e32 v83, v83, v126
	v_sub_f32_e32 v82, v82, v126
	v_mul_f32_e32 v244, v244, v127
	s_branch .LBB0_1083
